# combined micro-edit stack plus DPP reductions in the POST gated-norm loop and early scan start (loop begins once the first chunk's operands landed)
# baseline (speedup 1.0000x reference)
.LBB0_652:
	s_andn2_b64 vcc, exec, s[0:1]
	s_cbranch_vccnz .LBB0_704
	v_and_b32_e32 v14, 63, v206
	v_lshrrev_b32_e32 v15, 6, v206
	v_and_b32_e32 v64, 15, v14
	v_readfirstlane_b32 s11, v15
	v_lshrrev_b32_e32 v65, 4, v14
	v_lshlrev_b32_e32 v66, 2, v206
	ds_write_b32 v66, v0
	ds_write_b32 v66, v0 offset:2048
	ds_write_b32 v66, v0 offset:4096
	ds_write_b32 v66, v0 offset:6144
	ds_write_b32 v66, v0 offset:8192
	s_and_b32 s12, s11, 3
	s_and_b32 s13, s72, 7
	s_lshr_b32 s14, s72, 5
	s_bfe_u32 s15, s72, 0x20003
	s_lshl_b32 s16, s14, 3
	s_add_u32 s16, s16, s13
	s_lshl_b32 s17, s16, 21
	s_mov_b32 s18, 0x13800000
	s_cmp_lt_u32 s11, 4
	s_cselect_b32 s18, 0x11800000, s18
	s_add_u32 s18, s18, s17
	s_lshl_b32 s19, s12, 12
	s_add_u32 s18, s18, s19
	s_add_u32 s0, s70, s18
	s_addc_u32 s1, s71, 0
	s_lshl_b32 s19, s11, 11
	s_add_u32 s18, s17, s19
	s_add_u32 s18, s18, 0x15800000
	s_add_u32 s4, s70, s18
	s_addc_u32 s5, s71, 0
	s_lshl_b32 s18, s16, 9
	s_add_u32 s18, s18, 0x11500000
	s_add_u32 s6, s70, s18
	s_addc_u32 s7, s71, 0
	s_lshl_b32 s18, s15, 12
	s_lshl_b32 s19, s12, 9
	s_add_u32 s18, s18, s19
	s_add_u32 s18, s18, s17
	s_add_u32 s18, s18, 0x17800000
	s_lshl_b32 s19, s16, 20
	s_lshl_b32 s20, s12, 11
	s_add_u32 s19, s19, s20
	s_add_u32 s19, s19, 0x19800000
	s_cmp_lt_u32 s11, 4
	s_cselect_b32 s18, s18, s19
	s_add_u32 s2, s70, s18
	s_addc_u32 s3, s71, 0
	s_lshl_b32 s18, s14, 24
	s_lshl_b32 s19, s12, 15
	s_add_u32 s18, s18, s19
	s_lshl_b32 s19, s13, 8
	s_add_u32 s18, s18, s19
	s_lshl_b32 s19, s15, 6
	s_add_u32 s18, s18, s19
	s_add_u32 s18, s18, 0xb400000
	s_add_u32 s8, s70, s18
	s_addc_u32 s9, s71, 0
	v_lshlrev_b32_e32 v1, 4, v14
	v_mov_b32_e32 v3, 0
	v_mul_u32_u24_e32 v8, 0x110, v64
	v_mul_u32_u24_e32 v9, 0x90, v64
	v_lshl_add_u32 v11, v65, 3, v8
	v_lshl_add_u32 v10, v65, 3, v9
	v_lshl_add_u32 v8, v65, 4, v8
	v_lshl_add_u32 v9, v65, 4, v9
	s_lshl_b32 s18, s11, 5
	v_add_u32_e32 v11, s18, v11
	s_lshl_b32 s18, s12, 5
	v_add_u32_e32 v10, s18, v10
	s_mul_i32 s18, s12, 0x500
	s_add_u32 s18, s18, 0x5800
	v_mul_u32_u24_e32 v13, 0x140, v65
	v_lshl_add_u32 v13, v64, 1, v13
	v_add_u32_e32 v13, s18, v13
	v_lshrrev_b32_e32 v67, 2, v14
	v_and_b32_e32 v68, 3, v14
	v_mul_u32_u24_e32 v172, 0x50, v67
	v_lshl_add_u32 v172, v68, 4, v172
	v_add_u32_e32 v172, s18, v172
	v_lshlrev_b32_e32 v12, 11, v67
	v_lshl_add_u32 v12, v68, 4, v12
	v_mov_b32_e32 v16, 0
	v_mov_b32_e32 v17, 0
	v_mov_b32_e32 v18, 0
	v_mov_b32_e32 v19, 0
	v_mov_b32_e32 v20, 0
	v_mov_b32_e32 v21, 0
	v_mov_b32_e32 v22, 0
	v_mov_b32_e32 v23, 0
	s_cmp_lt_u32 s11, 4
	s_waitcnt lgkmcnt(0)
	s_barrier
	s_cbranch_scc0 .Lscan_O_path
	v_lshlrev_b32_e32 v2, 3, v14
	global_load_dwordx4 v[72:75], v1, s[0:1]
	global_load_dwordx4 v[76:79], v1, s[0:1] offset:1024
	global_load_dwordx4 v[80:83], v1, s[0:1] offset:2048
	global_load_dwordx4 v[84:87], v1, s[0:1] offset:3072
	global_load_dwordx2 v[88:89], v2, s[2:3]
	global_load_dwordx2 v[90:91], v2, s[2:3] offset:2048
	global_load_dwordx4 v[96:99], v1, s[4:5]
	global_load_dwordx4 v[100:103], v1, s[4:5] offset:1024
	global_load_dword v184, v3, s[6:7]
	v_add_u32_e32 v1, 0x4000, v1
	v_add_u32_e32 v2, 0x4000, v2
	v_add_u32_e32 v3, 4, v3
	global_load_dwordx4 v[104:107], v1, s[0:1]
	global_load_dwordx4 v[108:111], v1, s[0:1] offset:1024
	global_load_dwordx4 v[112:115], v1, s[0:1] offset:2048
	global_load_dwordx4 v[116:119], v1, s[0:1] offset:3072
	global_load_dwordx2 v[120:121], v2, s[2:3]
	global_load_dwordx2 v[122:123], v2, s[2:3] offset:2048
	global_load_dwordx4 v[128:131], v1, s[4:5]
	global_load_dwordx4 v[132:135], v1, s[4:5] offset:1024
	global_load_dword v185, v3, s[6:7]
	v_add_u32_e32 v1, 0x4000, v1
	v_add_u32_e32 v2, 0x4000, v2
	v_add_u32_e32 v3, 4, v3
	s_waitcnt vmcnt(9)
	s_movk_i32 s10, 32

.Lscan_O_path:
	v_lshlrev_b32_e32 v2, 4, v14
	s_cmp_lt_u32 s12, 2
	s_cbranch_scc1 .Lscan_P_path
	global_load_dwordx4 v[72:75], v1, s[0:1]
	global_load_dwordx4 v[76:79], v1, s[0:1] offset:1024
	global_load_dwordx4 v[80:83], v1, s[0:1] offset:2048
	global_load_dwordx4 v[84:87], v1, s[0:1] offset:3072
	global_load_dwordx4 v[88:91], v2, s[2:3]
	global_load_dwordx4 v[92:95], v2, s[2:3] offset:1024
	global_load_dwordx4 v[96:99], v1, s[4:5]
	global_load_dwordx4 v[100:103], v1, s[4:5] offset:1024
	global_load_dword v184, v3, s[6:7]
	v_add_u32_e32 v1, 0x4000, v1
	v_add_u32_e32 v2, 0x2000, v2
	v_add_u32_e32 v3, 4, v3
	global_load_dwordx4 v[104:107], v1, s[0:1]
	global_load_dwordx4 v[108:111], v1, s[0:1] offset:1024
	global_load_dwordx4 v[112:115], v1, s[0:1] offset:2048
	global_load_dwordx4 v[116:119], v1, s[0:1] offset:3072
	global_load_dwordx4 v[120:123], v2, s[2:3]
	global_load_dwordx4 v[124:127], v2, s[2:3] offset:1024
	global_load_dwordx4 v[128:131], v1, s[4:5]
	global_load_dwordx4 v[132:135], v1, s[4:5] offset:1024
	global_load_dword v185, v3, s[6:7]
	v_add_u32_e32 v1, 0x4000, v1
	v_add_u32_e32 v2, 0x2000, v2
	v_add_u32_e32 v3, 4, v3
	s_waitcnt vmcnt(9)
	s_movk_i32 s10, 32

.Lscan_P_path:
	global_load_dwordx4 v[72:75], v1, s[0:1]
	global_load_dwordx4 v[76:79], v1, s[0:1] offset:1024
	global_load_dwordx4 v[80:83], v1, s[0:1] offset:2048
	global_load_dwordx4 v[84:87], v1, s[0:1] offset:3072
	global_load_dwordx4 v[88:91], v2, s[2:3]
	global_load_dwordx4 v[96:99], v1, s[4:5]
	global_load_dwordx4 v[100:103], v1, s[4:5] offset:1024
	global_load_dword v184, v3, s[6:7]
	v_add_u32_e32 v1, 0x4000, v1
	v_add_u32_e32 v2, 0x2000, v2
	v_add_u32_e32 v3, 4, v3
	global_load_dwordx4 v[104:107], v1, s[0:1]
	global_load_dwordx4 v[108:111], v1, s[0:1] offset:1024
	global_load_dwordx4 v[112:115], v1, s[0:1] offset:2048
	global_load_dwordx4 v[116:119], v1, s[0:1] offset:3072
	global_load_dwordx4 v[120:123], v2, s[2:3]
	global_load_dwordx4 v[128:131], v1, s[4:5]
	global_load_dwordx4 v[132:135], v1, s[4:5] offset:1024
	global_load_dword v185, v3, s[6:7]
	v_add_u32_e32 v1, 0x4000, v1
	v_add_u32_e32 v2, 0x2000, v2
	v_add_u32_e32 v3, 4, v3
	s_waitcnt vmcnt(8)
	s_movk_i32 s10, 32

.LBB0_761:
	v_ashrrev_i32_e32 v12, 7, v1
	v_ashrrev_i32_e32 v13, 31, v12
	v_lshlrev_b64 v[28:29], 11, v[12:13]
	v_and_b32_e32 v14, 0x3f8, v10
	v_lshl_add_u64 v[12:13], s[2:3], 0, v[28:29]
	v_lshlrev_b32_e32 v30, 1, v14
	v_mov_b32_e32 v31, v0
	v_lshl_add_u64 v[12:13], v[12:13], 0, v[30:31]
	global_load_dwordx4 v[12:15], v[12:13], off nt
	v_lshl_add_u64 v[16:17], s[4:5], 0, v[28:29]
	v_lshl_add_u64 v[16:17], v[16:17], 0, v[30:31]
	global_load_dwordx4 v[16:19], v[16:17], off nt
	v_add_u32_e32 v1, s76, v1
	v_add_u32_e32 v10, s92, v10
	v_ashrrev_i32_e32 v60, 7, v1
	v_ashrrev_i32_e32 v61, 31, v60
	v_lshlrev_b64 v[76:77], 11, v[60:61]
	v_and_b32_e32 v62, 0x3f8, v10
	v_lshl_add_u64 v[60:61], s[2:3], 0, v[76:77]
	v_lshlrev_b32_e32 v78, 1, v62
	v_mov_b32_e32 v79, v0
	v_lshl_add_u64 v[60:61], v[60:61], 0, v[78:79]
	global_load_dwordx4 v[60:63], v[60:61], off nt
	v_lshl_add_u64 v[64:65], s[4:5], 0, v[76:77]
	v_lshl_add_u64 v[64:65], v[64:65], 0, v[78:79]
	global_load_dwordx4 v[64:67], v[64:65], off nt
	v_add_u32_e32 v1, s76, v1
	v_add_u32_e32 v10, s92, v10
	s_waitcnt vmcnt(3)
	v_and_b32_e32 v33, 0xffff0000, v15
	v_and_b32_e32 v37, 0xffff0000, v14
	v_lshlrev_b32_e32 v32, 16, v15
	v_lshlrev_b32_e32 v36, 16, v14
	v_mov_b32_e32 v38, v33
	v_mov_b32_e32 v39, v37
	v_mov_b32_e32 v14, v32
	v_mov_b32_e32 v15, v36
	v_pk_mul_f32 v[38:39], v[38:39], v[38:39]
	s_waitcnt vmcnt(2)
	v_lshlrev_b32_e32 v34, 16, v19
	v_pk_fma_f32 v[14:15], v[14:15], v[14:15], v[38:39]
	v_lshlrev_b32_e32 v38, 16, v18
	v_and_b32_e32 v39, 0xffff0000, v18
	v_mul_f32_e32 v11, 0xbfb8aa3b, v38
	v_exp_f32_e32 v18, v11
	v_mul_f32_e32 v11, 0xbfb8aa3b, v39
	v_and_b32_e32 v35, 0xffff0000, v19
	v_exp_f32_e32 v19, v11
	s_nop 0
	v_pk_add_f32 v[18:19], v[18:19], 1.0 op_sel_hi:[1,0]
	s_nop 0
	s_nop 0
	s_nop 0
	s_nop 0
	s_nop 0
	s_nop 0
	s_nop 0
	s_nop 0
	s_nop 0
	s_nop 0
	s_nop 0
	s_nop 0
	v_rcp_f32_e32 v19, v19
	s_nop 0
	s_nop 0
	s_nop 0
	s_nop 0
	s_nop 0
	s_nop 0
	s_nop 0
	s_nop 0
	s_nop 0
	s_nop 0
	s_nop 0
	v_lshlrev_b32_e32 v40, 16, v17
	v_rcp_f32_e32 v18, v18
	v_and_b32_e32 v41, 0xffff0000, v17
	v_mul_f32_e32 v11, 0xbfb8aa3b, v40
	v_exp_f32_e32 v42, v11
	v_mul_f32_e32 v11, 0xbfb8aa3b, v41
	v_exp_f32_e32 v43, v11
	v_pk_mul_f32 v[18:19], v[18:19], v[38:39]
	v_lshlrev_b32_e32 v38, 16, v13
	v_and_b32_e32 v39, 0xffff0000, v13
	v_pk_add_f32 v[42:43], v[42:43], 1.0 op_sel_hi:[1,0]
	s_nop 0
	s_nop 0
	s_nop 0
	s_nop 0
	s_nop 0
	s_nop 0
	s_nop 0
	s_nop 0
	s_nop 0
	s_nop 0
	s_nop 0
	s_nop 0
	v_rcp_f32_e32 v43, v43
	s_nop 0
	s_nop 0
	s_nop 0
	s_nop 0
	s_nop 0
	s_nop 0
	s_nop 0
	s_nop 0
	s_nop 0
	s_nop 0
	s_nop 0
	v_rcp_f32_e32 v42, v42
	s_nop 0
	v_pk_mul_f32 v[40:41], v[42:43], v[40:41]
	v_and_b32_e32 v43, 0xffff0000, v12
	v_lshlrev_b32_e32 v42, 16, v12
	v_mov_b32_e32 v44, v43
	v_mov_b32_e32 v45, v39
	v_mov_b32_e32 v12, v42
	v_mov_b32_e32 v13, v38
	v_pk_mul_f32 v[44:45], v[44:45], v[44:45]
	s_nop 0
	v_pk_fma_f32 v[12:13], v[12:13], v[12:13], v[44:45]
	v_lshlrev_b32_e32 v44, 16, v16
	v_and_b32_e32 v45, 0xffff0000, v16
	v_mul_f32_e32 v11, 0xbfb8aa3b, v44
	v_exp_f32_e32 v16, v11
	v_mul_f32_e32 v11, 0xbfb8aa3b, v45
	v_exp_f32_e32 v17, v11
	s_nop 0
	v_pk_add_f32 v[16:17], v[16:17], 1.0 op_sel_hi:[1,0]
	s_nop 0
	s_nop 0
	s_nop 0
	s_nop 0
	s_nop 0
	s_nop 0
	s_nop 0
	s_nop 0
	s_nop 0
	s_nop 0
	s_nop 0
	s_nop 0
	v_rcp_f32_e32 v17, v17
	s_nop 0
	s_nop 0
	s_nop 0
	s_nop 0
	s_nop 0
	s_nop 0
	s_nop 0
	s_nop 0
	s_nop 0
	s_nop 0
	s_nop 0
	v_rcp_f32_e32 v16, v16
	v_add_f32_e32 v11, v12, v13
	v_add_f32_e32 v11, v15, v11
	v_add_f32_e32 v11, v14, v11
	v_pk_mul_f32 v[16:17], v[16:17], v[44:45]
	s_nop 1
	v_add_f32_dpp v11, v11, v11 quad_perm:[1,0,3,2] row_mask:0xf bank_mask:0xf
	s_nop 1
	v_add_f32_dpp v11, v11, v11 quad_perm:[2,3,0,1] row_mask:0xf bank_mask:0xf
	s_nop 1
	v_add_f32_dpp v11, v11, v11 row_half_mirror row_mask:0xf bank_mask:0xf
	s_nop 1
	v_add_f32_dpp v11, v11, v11 row_mirror row_mask:0xf bank_mask:0xf
	v_fmamk_f32 v11, v11, 0x3c000000, v208
	v_cmp_gt_f32_e32 vcc, s51, v11
	v_mul_f32_e32 v12, 0x4b800000, v11
	s_nop 0
	v_cndmask_b32_e32 v11, v11, v12, vcc
	v_rsq_f32_e32 v11, v11
	s_nop 0
	v_mul_f32_e32 v12, 0x45800000, v11
	v_cndmask_b32_e32 v44, v11, v12, vcc
	v_pk_mul_f32 v[12:13], v[44:45], v[42:43] op_sel_hi:[0,1]
	v_pk_mul_f32 v[12:13], v[24:25], v[12:13]
	v_mul_f32_e32 v11, 0xbfb8aa3b, v34
	v_pk_mul_f32 v[12:13], v[16:17], v[12:13]
	v_exp_f32_e32 v16, v11
	v_mul_f32_e32 v11, 0xbfb8aa3b, v35
	v_pk_mul_f32 v[14:15], v[44:45], v[38:39] op_sel_hi:[0,1]
	v_exp_f32_e32 v17, v11
	v_pk_mul_f32 v[14:15], v[26:27], v[14:15]
	v_cvt_pk_bf16_f32 v12, v12, v13
	v_pk_mul_f32 v[14:15], v[40:41], v[14:15]
	v_pk_add_f32 v[16:17], v[16:17], 1.0 op_sel_hi:[1,0]
	v_cvt_pk_bf16_f32 v13, v14, v15
	v_pk_mul_f32 v[14:15], v[44:45], v[36:37] op_sel_hi:[0,1]
	v_pk_mul_f32 v[14:15], v[20:21], v[14:15]
	s_nop 0
	v_pk_mul_f32 v[14:15], v[18:19], v[14:15]
	v_pk_mul_f32 v[18:19], v[44:45], v[32:33] op_sel_hi:[0,1]
	v_cvt_pk_bf16_f32 v14, v14, v15
	s_nop 0
	v_pk_mul_f32 v[18:19], v[22:23], v[18:19]
	s_nop 0
	s_nop 0
	s_nop 0
	s_nop 0
	s_nop 0
	s_nop 0
	s_nop 0
	s_nop 0
	v_rcp_f32_e32 v17, v17
	s_nop 0
	s_nop 0
	s_mov_b32 s10, 0x1fffff
	s_nop 0
	s_nop 0
	s_nop 0
	s_nop 0
	s_nop 0
	s_nop 0
	s_nop 0
	s_nop 0
	v_rcp_f32_e32 v16, v16
	s_nop 0
	v_pk_mul_f32 v[16:17], v[16:17], v[34:35]
	v_cmp_lt_i32_e32 vcc, s10, v1
	v_pk_mul_f32 v[16:17], v[16:17], v[18:19]
	s_or_b64 s[8:9], vcc, s[8:9]
	v_cvt_pk_bf16_f32 v15, v16, v17
	v_lshl_add_u64 v[16:17], s[6:7], 0, v[28:29]
	v_lshl_add_u64 v[16:17], v[16:17], 0, v[30:31]
	global_store_dwordx4 v[16:17], v[12:15], off nt
	s_waitcnt vmcnt(2)
	v_and_b32_e32 v81, 0xffff0000, v63
	v_and_b32_e32 v85, 0xffff0000, v62
	v_lshlrev_b32_e32 v80, 16, v63
	v_lshlrev_b32_e32 v84, 16, v62
	v_mov_b32_e32 v86, v81
	v_mov_b32_e32 v87, v85
	v_mov_b32_e32 v62, v80
	v_mov_b32_e32 v63, v84
	v_pk_mul_f32 v[86:87], v[86:87], v[86:87]
	s_waitcnt vmcnt(1)
	v_lshlrev_b32_e32 v82, 16, v67
	v_pk_fma_f32 v[62:63], v[62:63], v[62:63], v[86:87]
	v_lshlrev_b32_e32 v86, 16, v66
	v_and_b32_e32 v87, 0xffff0000, v66
	v_mul_f32_e32 v59, 0xbfb8aa3b, v86
	v_exp_f32_e32 v66, v59
	v_mul_f32_e32 v59, 0xbfb8aa3b, v87
	v_and_b32_e32 v83, 0xffff0000, v67
	v_exp_f32_e32 v67, v59
	s_nop 0
	v_pk_add_f32 v[66:67], v[66:67], 1.0 op_sel_hi:[1,0]
	s_nop 0
	s_nop 0
	s_nop 0
	s_nop 0
	s_nop 0
	s_nop 0
	s_nop 0
	s_nop 0
	s_nop 0
	s_nop 0
	s_nop 0
	s_nop 0
	v_rcp_f32_e32 v67, v67
	s_nop 0
	s_nop 0
	s_nop 0
	s_nop 0
	s_nop 0
	s_nop 0
	s_nop 0
	s_nop 0
	s_nop 0
	s_nop 0
	s_nop 0
	v_lshlrev_b32_e32 v88, 16, v65
	v_rcp_f32_e32 v66, v66
	v_and_b32_e32 v89, 0xffff0000, v65
	v_mul_f32_e32 v59, 0xbfb8aa3b, v88
	v_exp_f32_e32 v90, v59
	v_mul_f32_e32 v59, 0xbfb8aa3b, v89
	v_exp_f32_e32 v91, v59
	v_pk_mul_f32 v[66:67], v[66:67], v[86:87]
	v_lshlrev_b32_e32 v86, 16, v61
	v_and_b32_e32 v87, 0xffff0000, v61
	v_pk_add_f32 v[90:91], v[90:91], 1.0 op_sel_hi:[1,0]
	s_nop 0
	s_nop 0
	s_nop 0
	s_nop 0
	s_nop 0
	s_nop 0
	s_nop 0
	s_nop 0
	s_nop 0
	s_nop 0
	s_nop 0
	s_nop 0
	v_rcp_f32_e32 v91, v91
	s_nop 0
	s_nop 0
	s_nop 0
	s_nop 0
	s_nop 0
	s_nop 0
	s_nop 0
	s_nop 0
	s_nop 0
	s_nop 0
	s_nop 0
	v_rcp_f32_e32 v90, v90
	s_nop 0
	v_pk_mul_f32 v[88:89], v[90:91], v[88:89]
	v_and_b32_e32 v91, 0xffff0000, v60
	v_lshlrev_b32_e32 v90, 16, v60
	v_mov_b32_e32 v92, v91
	v_mov_b32_e32 v93, v87
	v_mov_b32_e32 v60, v90
	v_mov_b32_e32 v61, v86
	v_pk_mul_f32 v[92:93], v[92:93], v[92:93]
	s_nop 0
	v_pk_fma_f32 v[60:61], v[60:61], v[60:61], v[92:93]
	v_lshlrev_b32_e32 v92, 16, v64
	v_and_b32_e32 v93, 0xffff0000, v64
	v_mul_f32_e32 v59, 0xbfb8aa3b, v92
	v_exp_f32_e32 v64, v59
	v_mul_f32_e32 v59, 0xbfb8aa3b, v93
	v_exp_f32_e32 v65, v59
	s_nop 0
	v_pk_add_f32 v[64:65], v[64:65], 1.0 op_sel_hi:[1,0]
	s_nop 0
	s_nop 0
	s_nop 0
	s_nop 0
	s_nop 0
	s_nop 0
	s_nop 0
	s_nop 0
	s_nop 0
	s_nop 0
	s_nop 0
	s_nop 0
	v_rcp_f32_e32 v65, v65
	s_nop 0
	s_nop 0
	s_nop 0
	s_nop 0
	s_nop 0
	s_nop 0
	s_nop 0
	s_nop 0
	s_nop 0
	s_nop 0
	s_nop 0
	v_rcp_f32_e32 v64, v64
	v_add_f32_e32 v59, v60, v61
	v_add_f32_e32 v59, v63, v59
	v_add_f32_e32 v59, v62, v59
	v_pk_mul_f32 v[64:65], v[64:65], v[92:93]
	s_nop 1
	v_add_f32_dpp v59, v59, v59 quad_perm:[1,0,3,2] row_mask:0xf bank_mask:0xf
	s_nop 1
	v_add_f32_dpp v59, v59, v59 quad_perm:[2,3,0,1] row_mask:0xf bank_mask:0xf
	s_nop 1
	v_add_f32_dpp v59, v59, v59 row_half_mirror row_mask:0xf bank_mask:0xf
	s_nop 1
	v_add_f32_dpp v59, v59, v59 row_mirror row_mask:0xf bank_mask:0xf
	v_fmamk_f32 v59, v59, 0x3c000000, v208
	v_cmp_gt_f32_e32 vcc, s51, v59
	v_mul_f32_e32 v60, 0x4b800000, v59
	s_nop 0
	v_cndmask_b32_e32 v59, v59, v60, vcc
	v_rsq_f32_e32 v59, v59
	s_nop 0
	v_mul_f32_e32 v60, 0x45800000, v59
	v_cndmask_b32_e32 v92, v59, v60, vcc
	v_pk_mul_f32 v[60:61], v[92:93], v[90:91] op_sel_hi:[0,1]
	v_pk_mul_f32 v[60:61], v[24:25], v[60:61]
	v_mul_f32_e32 v59, 0xbfb8aa3b, v82
	v_pk_mul_f32 v[60:61], v[64:65], v[60:61]
	v_exp_f32_e32 v64, v59
	v_mul_f32_e32 v59, 0xbfb8aa3b, v83
	v_pk_mul_f32 v[62:63], v[92:93], v[86:87] op_sel_hi:[0,1]
	v_exp_f32_e32 v65, v59
	v_pk_mul_f32 v[62:63], v[26:27], v[62:63]
	v_cvt_pk_bf16_f32 v60, v60, v61
	v_pk_mul_f32 v[62:63], v[88:89], v[62:63]
	v_pk_add_f32 v[64:65], v[64:65], 1.0 op_sel_hi:[1,0]
	v_cvt_pk_bf16_f32 v61, v62, v63
	v_pk_mul_f32 v[62:63], v[92:93], v[84:85] op_sel_hi:[0,1]
	v_pk_mul_f32 v[62:63], v[20:21], v[62:63]
	s_nop 0
	v_pk_mul_f32 v[62:63], v[66:67], v[62:63]
	v_pk_mul_f32 v[66:67], v[92:93], v[80:81] op_sel_hi:[0,1]
	v_cvt_pk_bf16_f32 v62, v62, v63
	s_nop 0
	v_pk_mul_f32 v[66:67], v[22:23], v[66:67]
	s_nop 0
	s_nop 0
	s_nop 0
	s_nop 0
	s_nop 0
	s_nop 0
	s_nop 0
	s_nop 0
	v_rcp_f32_e32 v65, v65
	s_nop 0
	s_nop 0
	s_mov_b32 s10, 0x1fffff
	s_nop 0
	s_nop 0
	s_nop 0
	s_nop 0
	s_nop 0
	s_nop 0
	s_nop 0
	s_nop 0
	v_rcp_f32_e32 v64, v64
	s_nop 0
	v_pk_mul_f32 v[64:65], v[64:65], v[82:83]
	v_cmp_lt_i32_e32 vcc, s10, v1
	v_pk_mul_f32 v[64:65], v[64:65], v[66:67]
	s_or_b64 s[8:9], vcc, s[8:9]
	v_cvt_pk_bf16_f32 v63, v64, v65
	v_lshl_add_u64 v[64:65], s[6:7], 0, v[76:77]
	v_lshl_add_u64 v[64:65], v[64:65], 0, v[78:79]
	global_store_dwordx4 v[64:65], v[60:63], off nt
	s_andn2_b64 exec, exec, s[8:9]
	s_cbranch_execnz .LBB0_761
